# v41 + diff-attention epilogue: 8-byte write-through row stores paired into 16-byte stores via v_permlane32_swap
# speedup vs baseline: 1.0067x; 1.0067x over previous
.LBB0_1614:
	s_cmpk_gt_u32 s0, 0xff
	s_waitcnt lgkmcnt(0)
	s_barrier
	s_cbranch_scc1 .LBB0_1595
	s_lshl_b32 s0, s0, 8
	v_lshl_add_u32 v5, v207, 2, 0
	s_and_b32 s1, s0, 0xc000
	v_add_u32_e32 v6, s1, v5
	ds_read2st64_b32 v[10:11], v6 offset1:1
	ds_read2st64_b32 v[14:15], v6 offset0:2 offset1:3
	ds_read2st64_b32 v[86:87], v6 offset0:4 offset1:5
	ds_read2st64_b32 v[88:89], v6 offset0:6 offset1:7
	ds_read2st64_b32 v[90:91], v6 offset0:8 offset1:9
	ds_read2st64_b32 v[92:93], v6 offset0:10 offset1:11
	ds_read2st64_b32 v[94:95], v6 offset0:12 offset1:13
	ds_read2st64_b32 v[96:97], v6 offset0:14 offset1:15
	ds_read2st64_b32 v[98:99], v6 offset0:16 offset1:17
	ds_read2st64_b32 v[100:101], v6 offset0:18 offset1:19
	ds_read2st64_b32 v[102:103], v6 offset0:20 offset1:21
	ds_read2st64_b32 v[104:105], v6 offset0:22 offset1:23
	ds_read2st64_b32 v[106:107], v6 offset0:24 offset1:25
	ds_read2st64_b32 v[108:109], v6 offset0:26 offset1:27
	ds_read2st64_b32 v[110:111], v6 offset0:28 offset1:29
	ds_read2st64_b32 v[112:113], v6 offset0:30 offset1:31
	ds_read2st64_b32 v[114:115], v6 offset0:32 offset1:33
	ds_read2st64_b32 v[116:117], v6 offset0:34 offset1:35
	ds_read2st64_b32 v[118:119], v6 offset0:36 offset1:37
	ds_read2st64_b32 v[120:121], v6 offset0:38 offset1:39
	ds_read2st64_b32 v[122:123], v6 offset0:40 offset1:41
	ds_read2st64_b32 v[124:125], v6 offset0:42 offset1:43
	ds_read2st64_b32 v[126:127], v6 offset0:44 offset1:45
	ds_read2st64_b32 v[128:129], v6 offset0:46 offset1:47
	ds_read2st64_b32 v[12:13], v6 offset0:56 offset1:57
	ds_read2st64_b32 v[130:131], v6 offset0:58 offset1:59
	ds_read2st64_b32 v[2:3], v6 offset0:60 offset1:61
	ds_read_b32 v4, v6 offset:15872
	s_waitcnt lgkmcnt(14)
	v_pk_mul_f32 v[10:11], v[160:161], v[10:11]
	s_or_b32 s0, s0, 0x3f00
	v_pk_fma_f32 v[82:83], v[64:65], v[0:1], v[10:11] op_sel_hi:[1,0,1] neg_lo:[0,0,1] neg_hi:[0,0,1]
	v_pk_mul_f32 v[10:11], v[160:161], v[88:89]
	v_add_u32_e32 v5, s0, v5
	v_pk_fma_f32 v[70:71], v[70:71], v[0:1], v[10:11] op_sel_hi:[1,0,1] neg_lo:[0,0,1] neg_hi:[0,0,1]
	v_pk_mul_f32 v[10:11], v[160:161], v[86:87]
	ds_read_b32 v5, v5
	ds_read2st64_b32 v[132:133], v6 offset0:48 offset1:49
	ds_read2st64_b32 v[134:135], v6 offset0:50 offset1:51
	ds_read2st64_b32 v[136:137], v6 offset0:52 offset1:53
	ds_read2st64_b32 v[138:139], v6 offset0:54 offset1:55
	v_pk_fma_f32 v[86:87], v[68:69], v[0:1], v[10:11] op_sel_hi:[1,0,1] neg_lo:[0,0,1] neg_hi:[0,0,1]
	v_pk_mul_f32 v[10:11], v[160:161], v[92:93]
	s_waitcnt lgkmcnt(6)
	v_pk_mul_f32 v[2:3], v[160:161], v[2:3]
	v_pk_fma_f32 v[74:75], v[74:75], v[0:1], v[10:11] op_sel_hi:[1,0,1] neg_lo:[0,0,1] neg_hi:[0,0,1]
	v_pk_mul_f32 v[10:11], v[160:161], v[90:91]
	v_pk_fma_f32 v[6:7], v[28:29], v[0:1], v[2:3] op_sel_hi:[1,0,1] neg_lo:[0,0,1] neg_hi:[0,0,1]
	v_pk_fma_f32 v[90:91], v[72:73], v[0:1], v[10:11] op_sel_hi:[1,0,1] neg_lo:[0,0,1] neg_hi:[0,0,1]
	v_pk_mul_f32 v[10:11], v[160:161], v[96:97]
	s_waitcnt lgkmcnt(4)
	v_pk_mul_f32 v[2:3], v[160:161], v[4:5]
	v_pk_fma_f32 v[68:69], v[78:79], v[0:1], v[10:11] op_sel_hi:[1,0,1] neg_lo:[0,0,1] neg_hi:[0,0,1]
	v_pk_mul_f32 v[10:11], v[160:161], v[94:95]
	v_pk_fma_f32 v[8:9], v[30:31], v[0:1], v[2:3] op_sel_hi:[1,0,1] neg_lo:[0,0,1] neg_hi:[0,0,1]
	v_pk_fma_f32 v[88:89], v[76:77], v[0:1], v[10:11] op_sel_hi:[1,0,1] neg_lo:[0,0,1] neg_hi:[0,0,1]
	v_pk_mul_f32 v[10:11], v[160:161], v[100:101]
	v_pk_mul_f32 v[14:15], v[160:161], v[14:15]
	v_pk_fma_f32 v[64:65], v[50:51], v[0:1], v[10:11] op_sel_hi:[1,0,1] neg_lo:[0,0,1] neg_hi:[0,0,1]
	v_pk_mul_f32 v[10:11], v[160:161], v[98:99]
	v_pk_fma_f32 v[66:67], v[66:67], v[0:1], v[14:15] op_sel_hi:[1,0,1] neg_lo:[0,0,1] neg_hi:[0,0,1]
	v_pk_fma_f32 v[78:79], v[48:49], v[0:1], v[10:11] op_sel_hi:[1,0,1] neg_lo:[0,0,1] neg_hi:[0,0,1]
	v_pk_mul_f32 v[10:11], v[160:161], v[104:105]
	v_pk_mul_f32 v[142:143], v[82:83], v[82:83]
	v_pk_fma_f32 v[54:55], v[54:55], v[0:1], v[10:11] op_sel_hi:[1,0,1] neg_lo:[0,0,1] neg_hi:[0,0,1]
	v_pk_mul_f32 v[10:11], v[160:161], v[102:103]
	v_pk_mul_f32 v[12:13], v[160:161], v[12:13]
	v_pk_fma_f32 v[76:77], v[52:53], v[0:1], v[10:11] op_sel_hi:[1,0,1] neg_lo:[0,0,1] neg_hi:[0,0,1]
	v_pk_mul_f32 v[10:11], v[160:161], v[108:109]
	global_load_dwordx4 v[2:5], v162, s[38:39]
	global_load_dwordx4 v[152:155], v162, s[38:39] offset:32
	global_load_dwordx4 v[156:159], v162, s[38:39] offset:64
	global_load_dwordx4 v[168:171], v162, s[38:39] offset:96
	global_load_dwordx4 v[172:175], v162, s[38:39] offset:128
	global_load_dwordx4 v[176:179], v162, s[38:39] offset:160
	global_load_dwordx4 v[180:183], v162, s[38:39] offset:192
	global_load_dwordx4 v[184:187], v162, s[38:39] offset:224
	global_load_dwordx4 v[188:191], v162, s[38:39] offset:256
	global_load_dwordx4 v[192:195], v162, s[38:39] offset:288
	global_load_dwordx4 v[196:199], v162, s[38:39] offset:320
	v_pk_fma_f32 v[52:53], v[58:59], v[0:1], v[10:11] op_sel_hi:[1,0,1] neg_lo:[0,0,1] neg_hi:[0,0,1]
	v_pk_mul_f32 v[10:11], v[160:161], v[106:107]
	v_pk_mul_f32 v[140:141], v[66:67], v[66:67]
	v_pk_fma_f32 v[72:73], v[56:57], v[0:1], v[10:11] op_sel_hi:[1,0,1] neg_lo:[0,0,1] neg_hi:[0,0,1]
	v_pk_mul_f32 v[10:11], v[160:161], v[112:113]
	v_pk_fma_f32 v[12:13], v[24:25], v[0:1], v[12:13] op_sel_hi:[1,0,1] neg_lo:[0,0,1] neg_hi:[0,0,1]
	v_pk_fma_f32 v[50:51], v[62:63], v[0:1], v[10:11] op_sel_hi:[1,0,1] neg_lo:[0,0,1] neg_hi:[0,0,1]
	v_pk_mul_f32 v[10:11], v[160:161], v[110:111]
	v_pk_mul_f32 v[146:147], v[86:87], v[86:87]
	v_pk_fma_f32 v[60:61], v[60:61], v[0:1], v[10:11] op_sel_hi:[1,0,1] neg_lo:[0,0,1] neg_hi:[0,0,1]
	v_pk_mul_f32 v[10:11], v[160:161], v[116:117]
	v_pk_mul_f32 v[144:145], v[70:71], v[70:71]
	v_pk_fma_f32 v[48:49], v[34:35], v[0:1], v[10:11] op_sel_hi:[1,0,1] neg_lo:[0,0,1] neg_hi:[0,0,1]
	v_pk_mul_f32 v[10:11], v[160:161], v[114:115]
	v_pk_mul_f32 v[148:149], v[90:91], v[90:91]
	v_pk_fma_f32 v[58:59], v[32:33], v[0:1], v[10:11] op_sel_hi:[1,0,1] neg_lo:[0,0,1] neg_hi:[0,0,1]
	v_pk_mul_f32 v[10:11], v[160:161], v[120:121]
	v_pk_mul_f32 v[92:93], v[74:75], v[74:75]
	v_pk_fma_f32 v[32:33], v[38:39], v[0:1], v[10:11] op_sel_hi:[1,0,1] neg_lo:[0,0,1] neg_hi:[0,0,1]
	v_pk_mul_f32 v[10:11], v[160:161], v[118:119]
	v_pk_mul_f32 v[94:95], v[88:89], v[88:89]
	v_pk_fma_f32 v[56:57], v[36:37], v[0:1], v[10:11] op_sel_hi:[1,0,1] neg_lo:[0,0,1] neg_hi:[0,0,1]
	v_pk_mul_f32 v[10:11], v[160:161], v[124:125]
	v_pk_mul_f32 v[96:97], v[68:69], v[68:69]
	v_pk_fma_f32 v[30:31], v[42:43], v[0:1], v[10:11] op_sel_hi:[1,0,1] neg_lo:[0,0,1] neg_hi:[0,0,1]
	v_pk_mul_f32 v[10:11], v[160:161], v[122:123]
	v_pk_mul_f32 v[98:99], v[78:79], v[78:79]
	v_pk_fma_f32 v[38:39], v[40:41], v[0:1], v[10:11] op_sel_hi:[1,0,1] neg_lo:[0,0,1] neg_hi:[0,0,1]
	v_pk_mul_f32 v[10:11], v[160:161], v[128:129]
	v_pk_mul_f32 v[100:101], v[64:65], v[64:65]
	v_pk_fma_f32 v[28:29], v[46:47], v[0:1], v[10:11] op_sel_hi:[1,0,1] neg_lo:[0,0,1] neg_hi:[0,0,1]
	v_pk_mul_f32 v[10:11], v[160:161], v[126:127]
	v_pk_mul_f32 v[102:103], v[76:77], v[76:77]
	v_pk_fma_f32 v[36:37], v[44:45], v[0:1], v[10:11] op_sel_hi:[1,0,1] neg_lo:[0,0,1] neg_hi:[0,0,1]
	s_waitcnt lgkmcnt(2)
	v_pk_mul_f32 v[10:11], v[160:161], v[134:135]
	v_pk_mul_f32 v[104:105], v[54:55], v[54:55]
	v_pk_fma_f32 v[18:19], v[18:19], v[0:1], v[10:11] op_sel_hi:[1,0,1] neg_lo:[0,0,1] neg_hi:[0,0,1]
	v_pk_mul_f32 v[10:11], v[160:161], v[132:133]
	v_pk_mul_f32 v[106:107], v[72:73], v[72:73]
	v_pk_fma_f32 v[34:35], v[16:17], v[0:1], v[10:11] op_sel_hi:[1,0,1] neg_lo:[0,0,1] neg_hi:[0,0,1]
	s_waitcnt lgkmcnt(0)
	v_pk_mul_f32 v[10:11], v[160:161], v[138:139]
	v_pk_mul_f32 v[108:109], v[52:53], v[52:53]
	v_pk_fma_f32 v[14:15], v[22:23], v[0:1], v[10:11] op_sel_hi:[1,0,1] neg_lo:[0,0,1] neg_hi:[0,0,1]
	v_pk_mul_f32 v[10:11], v[160:161], v[136:137]
	v_pk_mul_f32 v[110:111], v[60:61], v[60:61]
	v_pk_fma_f32 v[16:17], v[20:21], v[0:1], v[10:11] op_sel_hi:[1,0,1] neg_lo:[0,0,1] neg_hi:[0,0,1]
	v_pk_mul_f32 v[10:11], v[160:161], v[130:131]
	v_pk_mul_f32 v[62:63], v[50:51], v[50:51]
	v_pk_fma_f32 v[10:11], v[26:27], v[0:1], v[10:11] op_sel_hi:[1,0,1] neg_lo:[0,0,1] neg_hi:[0,0,1]
	v_add_f32_e32 v0, v142, v143
	v_add_f32_e32 v0, v0, v140
	v_add_f32_e32 v0, v0, v141
	v_add_f32_e32 v0, v0, v146
	v_add_f32_e32 v0, v0, v147
	v_add_f32_e32 v0, v0, v144
	v_add_f32_e32 v0, v0, v145
	v_add_f32_e32 v0, v0, v148
	v_add_f32_e32 v0, v0, v149
	v_add_f32_e32 v0, v0, v92
	v_add_f32_e32 v0, v0, v93
	v_add_f32_e32 v0, v0, v94
	v_add_f32_e32 v0, v0, v95
	v_add_f32_e32 v0, v0, v96
	v_add_f32_e32 v0, v0, v97
	v_add_f32_e32 v0, v0, v98
	v_add_f32_e32 v0, v0, v99
	v_add_f32_e32 v0, v0, v100
	v_add_f32_e32 v0, v0, v101
	v_add_f32_e32 v0, v0, v102
	v_add_f32_e32 v0, v0, v103
	v_add_f32_e32 v0, v0, v104
	v_add_f32_e32 v0, v0, v105
	v_add_f32_e32 v0, v0, v106
	v_add_f32_e32 v0, v0, v107
	v_add_f32_e32 v0, v0, v108
	v_add_f32_e32 v0, v0, v109
	v_add_f32_e32 v0, v0, v110
	v_add_f32_e32 v0, v0, v111
	v_add_f32_e32 v0, v0, v62
	v_pk_mul_f32 v[114:115], v[58:59], v[58:59]
	v_add_f32_e32 v0, v0, v63
	v_add_f32_e32 v0, v0, v114
	v_pk_mul_f32 v[112:113], v[48:49], v[48:49]
	v_add_f32_e32 v0, v0, v115
	v_add_f32_e32 v0, v0, v112
	v_pk_mul_f32 v[118:119], v[56:57], v[56:57]
	v_add_f32_e32 v0, v0, v113
	v_add_f32_e32 v0, v0, v118
	v_pk_mul_f32 v[116:117], v[32:33], v[32:33]
	v_add_f32_e32 v0, v0, v119
	v_add_f32_e32 v0, v0, v116
	v_pk_mul_f32 v[40:41], v[38:39], v[38:39]
	v_add_f32_e32 v0, v0, v117
	v_add_f32_e32 v0, v0, v40
	v_pk_mul_f32 v[42:43], v[30:31], v[30:31]
	v_add_f32_e32 v0, v0, v41
	v_add_f32_e32 v0, v0, v42
	v_pk_mul_f32 v[44:45], v[36:37], v[36:37]
	v_add_f32_e32 v0, v0, v43
	v_add_f32_e32 v0, v0, v44
	v_pk_mul_f32 v[46:47], v[28:29], v[28:29]
	v_add_f32_e32 v0, v0, v45
	v_add_f32_e32 v0, v0, v46
	v_pk_mul_f32 v[122:123], v[34:35], v[34:35]
	v_add_f32_e32 v0, v0, v47
	v_add_f32_e32 v0, v0, v122
	v_pk_mul_f32 v[120:121], v[18:19], v[18:19]
	v_add_f32_e32 v0, v0, v123
	v_add_f32_e32 v0, v0, v120
	v_pk_mul_f32 v[20:21], v[16:17], v[16:17]
	v_add_f32_e32 v0, v0, v121
	v_add_f32_e32 v0, v0, v20
	v_pk_mul_f32 v[22:23], v[14:15], v[14:15]
	v_add_f32_e32 v0, v0, v21
	v_add_f32_e32 v0, v0, v22
	v_pk_mul_f32 v[24:25], v[12:13], v[12:13]
	v_add_f32_e32 v0, v0, v23
	v_add_f32_e32 v0, v0, v24
	v_pk_mul_f32 v[26:27], v[10:11], v[10:11]
	v_add_f32_e32 v0, v0, v25
	v_add_f32_e32 v0, v0, v26
	v_pk_mul_f32 v[80:81], v[6:7], v[6:7]
	v_add_f32_e32 v0, v0, v27
	v_add_f32_e32 v0, v0, v80
	v_pk_mul_f32 v[84:85], v[8:9], v[8:9]
	v_add_f32_e32 v0, v0, v81
	v_add_f32_e32 v0, v0, v84
	v_add_f32_e32 v22, v0, v85
	ds_bpermute_b32 v23, v163, v22
	v_lshlrev_b32_e32 v0, 1, v164
	v_lshl_add_u64 v[20:21], s[46:47], 0, v[0:1]
	v_lshl_add_u64 v[20:21], v[20:21], 0, v[166:167]
	s_mov_b64 s[0:1], 0x80
	s_waitcnt lgkmcnt(0)
	v_add_f32_e32 v0, v22, v23
	v_fmamk_f32 v0, v0, 0x3c000000, v205
	v_mul_f32_e32 v22, 0x4b800000, v0
	v_cmp_gt_f32_e32 vcc, s58, v0
	s_nop 1
	v_cndmask_b32_e32 v0, v0, v22, vcc
	v_rsq_f32_e32 v22, v0
	v_lshlrev_b32_e32 v0, 4, v165
	v_lshl_add_u64 v[20:21], v[20:21], 0, v[0:1]
	v_mul_f32_e32 v0, 0x45800000, v22
	v_cndmask_b32_e32 v0, v22, v0, vcc
	v_mul_f32_e32 v0, 0x3f077f5a, v0
	v_pk_mul_f32 v[22:23], v[82:83], v[0:1] op_sel_hi:[1,0]
	v_pk_mul_f32 v[24:25], v[86:87], v[0:1] op_sel_hi:[1,0]
	s_waitcnt vmcnt(0)
	v_pk_mul_f32 v[2:3], v[2:3], v[22:23]
	v_pk_mul_f32 v[22:23], v[66:67], v[0:1] op_sel_hi:[1,0]
	v_cvt_pk_bf16_f32 v2, v2, v3
	v_pk_mul_f32 v[4:5], v[4:5], v[22:23]
	v_lshl_add_u64 v[22:23], v[20:21], 0, 16
	v_cvt_pk_bf16_f32 v3, v4, v5
	v_mov_b32_e32 v236, v2
	v_mov_b32_e32 v237, v3
	v_mov_b64_e32 v[200:201], v[20:21]
	s_nop 1
	v_mov_b64_e32 v[2:3], v[152:153]
	v_mov_b64_e32 v[4:5], v[154:155]
	v_pk_mul_f32 v[26:27], v[74:75], v[0:1] op_sel_hi:[1,0]
	v_pk_mul_f32 v[18:19], v[18:19], v[0:1] op_sel_hi:[1,0]
	v_pk_mul_f32 v[16:17], v[16:17], v[0:1] op_sel_hi:[1,0]
	v_pk_mul_f32 v[14:15], v[14:15], v[0:1] op_sel_hi:[1,0]
	v_pk_mul_f32 v[12:13], v[12:13], v[0:1] op_sel_hi:[1,0]
	v_pk_mul_f32 v[10:11], v[10:11], v[0:1] op_sel_hi:[1,0]
	v_pk_mul_f32 v[6:7], v[6:7], v[0:1] op_sel_hi:[1,0]
	v_pk_mul_f32 v[8:9], v[8:9], v[0:1] op_sel_hi:[1,0]
	v_pk_mul_f32 v[2:3], v[2:3], v[24:25]
	v_pk_mul_f32 v[24:25], v[70:71], v[0:1] op_sel_hi:[1,0]
	v_cvt_pk_bf16_f32 v2, v2, v3
	v_pk_mul_f32 v[4:5], v[4:5], v[24:25]
	v_pk_mul_f32 v[24:25], v[90:91], v[0:1] op_sel_hi:[1,0]
	v_cvt_pk_bf16_f32 v3, v4, v5
	v_mov_b32_e32 v238, v2
	v_mov_b32_e32 v239, v3
	s_nop 1
	v_permlane32_swap_b32_e32 v236, v238
	v_permlane32_swap_b32_e32 v237, v239
	global_store_dwordx4 v[200:201], v[236:239], off sc1
	s_nop 1
	v_mov_b64_e32 v[2:3], v[156:157]
	v_mov_b64_e32 v[4:5], v[158:159]
	v_lshl_add_u64 v[22:23], v[20:21], 0, 32
	v_pk_mul_f32 v[2:3], v[2:3], v[24:25]
	v_pk_mul_f32 v[4:5], v[4:5], v[26:27]
	v_cvt_pk_bf16_f32 v2, v2, v3
	v_cvt_pk_bf16_f32 v3, v4, v5
	v_mov_b32_e32 v236, v2
	v_mov_b32_e32 v237, v3
	v_mov_b64_e32 v[200:201], v[22:23]
	s_nop 1
	v_mov_b64_e32 v[2:3], v[168:169]
	v_mov_b64_e32 v[4:5], v[170:171]
	v_pk_mul_f32 v[24:25], v[88:89], v[0:1] op_sel_hi:[1,0]
	v_pk_mul_f32 v[26:27], v[68:69], v[0:1] op_sel_hi:[1,0]
	v_lshl_add_u64 v[22:23], v[20:21], 0, 48
	v_pk_mul_f32 v[2:3], v[2:3], v[24:25]
	v_pk_mul_f32 v[4:5], v[4:5], v[26:27]
	v_cvt_pk_bf16_f32 v2, v2, v3
	v_cvt_pk_bf16_f32 v3, v4, v5
	v_mov_b32_e32 v238, v2
	v_mov_b32_e32 v239, v3
	s_nop 1
	v_permlane32_swap_b32_e32 v236, v238
	v_permlane32_swap_b32_e32 v237, v239
	global_store_dwordx4 v[200:201], v[236:239], off sc1
	s_nop 1
	v_mov_b64_e32 v[2:3], v[172:173]
	v_mov_b64_e32 v[4:5], v[174:175]
	v_pk_mul_f32 v[24:25], v[78:79], v[0:1] op_sel_hi:[1,0]
	v_pk_mul_f32 v[26:27], v[64:65], v[0:1] op_sel_hi:[1,0]
	v_lshl_add_u64 v[22:23], v[20:21], 0, 64
	v_pk_mul_f32 v[2:3], v[2:3], v[24:25]
	v_pk_mul_f32 v[4:5], v[4:5], v[26:27]
	v_cvt_pk_bf16_f32 v2, v2, v3
	v_cvt_pk_bf16_f32 v3, v4, v5
	v_mov_b32_e32 v236, v2
	v_mov_b32_e32 v237, v3
	v_mov_b64_e32 v[200:201], v[22:23]
	s_nop 1
	v_mov_b64_e32 v[2:3], v[176:177]
	v_mov_b64_e32 v[4:5], v[178:179]
	global_load_dwordx4 v[152:155], v162, s[38:39] offset:352
	global_load_dwordx4 v[156:159], v162, s[38:39] offset:384
	global_load_dwordx4 v[168:171], v162, s[38:39] offset:416
	global_load_dwordx4 v[172:175], v162, s[38:39] offset:448
	global_load_dwordx4 v[176:179], v162, s[38:39] offset:480
	v_pk_mul_f32 v[24:25], v[76:77], v[0:1] op_sel_hi:[1,0]
	v_pk_mul_f32 v[26:27], v[54:55], v[0:1] op_sel_hi:[1,0]
	v_lshl_add_u64 v[22:23], v[20:21], 0, s[42:43]
	v_pk_mul_f32 v[2:3], v[2:3], v[24:25]
	v_pk_mul_f32 v[4:5], v[4:5], v[26:27]
	v_cvt_pk_bf16_f32 v2, v2, v3
	v_cvt_pk_bf16_f32 v3, v4, v5
	v_mov_b32_e32 v238, v2
	v_mov_b32_e32 v239, v3
	s_nop 1
	v_permlane32_swap_b32_e32 v236, v238
	v_permlane32_swap_b32_e32 v237, v239
	global_store_dwordx4 v[200:201], v[236:239], off sc1
	s_nop 1
	v_mov_b64_e32 v[2:3], v[180:181]
	v_mov_b64_e32 v[4:5], v[182:183]
	v_pk_mul_f32 v[24:25], v[72:73], v[0:1] op_sel_hi:[1,0]
	v_pk_mul_f32 v[26:27], v[52:53], v[0:1] op_sel_hi:[1,0]
	v_lshl_add_u64 v[22:23], v[20:21], 0, s[44:45]
	v_pk_mul_f32 v[2:3], v[2:3], v[24:25]
	v_pk_mul_f32 v[4:5], v[4:5], v[26:27]
	v_cvt_pk_bf16_f32 v2, v2, v3
	v_cvt_pk_bf16_f32 v3, v4, v5
	v_mov_b32_e32 v236, v2
	v_mov_b32_e32 v237, v3
	v_mov_b64_e32 v[200:201], v[22:23]
	s_nop 1
	v_mov_b64_e32 v[2:3], v[184:185]
	v_mov_b64_e32 v[4:5], v[186:187]
	v_pk_mul_f32 v[24:25], v[60:61], v[0:1] op_sel_hi:[1,0]
	v_pk_mul_f32 v[26:27], v[50:51], v[0:1] op_sel_hi:[1,0]
	v_lshl_add_u64 v[22:23], v[20:21], 0, s[52:53]
	v_pk_mul_f32 v[2:3], v[24:25], v[2:3]
	v_pk_mul_f32 v[4:5], v[26:27], v[4:5]
	v_cvt_pk_bf16_f32 v2, v2, v3
	v_cvt_pk_bf16_f32 v3, v4, v5
	v_mov_b32_e32 v238, v2
	v_mov_b32_e32 v239, v3
	s_nop 1
	v_permlane32_swap_b32_e32 v236, v238
	v_permlane32_swap_b32_e32 v237, v239
	global_store_dwordx4 v[200:201], v[236:239], off sc1
	s_nop 1
	v_mov_b64_e32 v[2:3], v[188:189]
	v_mov_b64_e32 v[4:5], v[190:191]
	v_pk_mul_f32 v[24:25], v[58:59], v[0:1] op_sel_hi:[1,0]
	v_pk_mul_f32 v[26:27], v[48:49], v[0:1] op_sel_hi:[1,0]
	v_lshl_add_u64 v[22:23], v[20:21], 0, s[0:1]
	s_mov_b64 s[0:1], 0x90
	v_pk_mul_f32 v[2:3], v[24:25], v[2:3]
	v_pk_mul_f32 v[4:5], v[26:27], v[4:5]
	v_cvt_pk_bf16_f32 v2, v2, v3
	v_cvt_pk_bf16_f32 v3, v4, v5
	v_mov_b32_e32 v236, v2
	v_mov_b32_e32 v237, v3
	v_mov_b64_e32 v[200:201], v[22:23]
	s_nop 1
	v_mov_b64_e32 v[2:3], v[192:193]
	v_mov_b64_e32 v[4:5], v[194:195]
	v_pk_mul_f32 v[24:25], v[56:57], v[0:1] op_sel_hi:[1,0]
	v_pk_mul_f32 v[26:27], v[32:33], v[0:1] op_sel_hi:[1,0]
	v_lshl_add_u64 v[22:23], v[20:21], 0, s[0:1]
	s_mov_b64 s[0:1], 0xa0
	v_pk_mul_f32 v[2:3], v[24:25], v[2:3]
	v_pk_mul_f32 v[4:5], v[26:27], v[4:5]
	v_cvt_pk_bf16_f32 v2, v2, v3
	v_cvt_pk_bf16_f32 v3, v4, v5
	v_mov_b32_e32 v238, v2
	v_mov_b32_e32 v239, v3
	s_nop 1
	v_permlane32_swap_b32_e32 v236, v238
	v_permlane32_swap_b32_e32 v237, v239
	global_store_dwordx4 v[200:201], v[236:239], off sc1
	s_nop 1
	v_mov_b64_e32 v[2:3], v[196:197]
	v_mov_b64_e32 v[4:5], v[198:199]
	v_pk_mul_f32 v[24:25], v[38:39], v[0:1] op_sel_hi:[1,0]
	v_pk_mul_f32 v[26:27], v[30:31], v[0:1] op_sel_hi:[1,0]
	v_lshl_add_u64 v[22:23], v[20:21], 0, s[0:1]
	s_mov_b64 s[0:1], 0xb0
	v_pk_mul_f32 v[2:3], v[24:25], v[2:3]
	v_pk_mul_f32 v[4:5], v[26:27], v[4:5]
	v_cvt_pk_bf16_f32 v2, v2, v3
	v_cvt_pk_bf16_f32 v3, v4, v5
	v_mov_b32_e32 v236, v2
	v_mov_b32_e32 v237, v3
	v_mov_b64_e32 v[200:201], v[22:23]
	s_nop 1
	s_waitcnt vmcnt(6)
	v_mov_b64_e32 v[2:3], v[152:153]
	v_mov_b64_e32 v[4:5], v[154:155]
	v_pk_mul_f32 v[24:25], v[36:37], v[0:1] op_sel_hi:[1,0]
	v_pk_mul_f32 v[26:27], v[28:29], v[0:1] op_sel_hi:[1,0]
	v_lshl_add_u64 v[22:23], v[20:21], 0, s[0:1]
	s_mov_b64 s[0:1], 0xc0
	v_pk_mul_f32 v[2:3], v[24:25], v[2:3]
	v_pk_mul_f32 v[4:5], v[26:27], v[4:5]
	v_cvt_pk_bf16_f32 v2, v2, v3
	v_cvt_pk_bf16_f32 v3, v4, v5
	v_mov_b32_e32 v238, v2
	v_mov_b32_e32 v239, v3
	s_nop 1
	v_permlane32_swap_b32_e32 v236, v238
	v_permlane32_swap_b32_e32 v237, v239
	global_store_dwordx4 v[200:201], v[236:239], off sc1
	s_nop 1
	v_mov_b64_e32 v[2:3], v[156:157]
	v_mov_b64_e32 v[4:5], v[158:159]
	v_pk_mul_f32 v[24:25], v[34:35], v[0:1] op_sel_hi:[1,0]
	v_lshl_add_u64 v[22:23], v[20:21], 0, s[0:1]
	s_mov_b64 s[0:1], 0xd0
	v_pk_mul_f32 v[2:3], v[24:25], v[2:3]
	v_pk_mul_f32 v[4:5], v[18:19], v[4:5]
	v_cvt_pk_bf16_f32 v2, v2, v3
	v_cvt_pk_bf16_f32 v3, v4, v5
	v_mov_b32_e32 v236, v2
	v_mov_b32_e32 v237, v3
	v_mov_b64_e32 v[200:201], v[22:23]
	s_nop 1
	v_mov_b64_e32 v[2:3], v[168:169]
	v_mov_b64_e32 v[4:5], v[170:171]
	v_lshl_add_u64 v[18:19], v[20:21], 0, s[0:1]
	s_mov_b64 s[0:1], 0xe0
	v_pk_mul_f32 v[2:3], v[16:17], v[2:3]
	v_pk_mul_f32 v[4:5], v[14:15], v[4:5]
	v_cvt_pk_bf16_f32 v2, v2, v3
	v_cvt_pk_bf16_f32 v3, v4, v5
	v_mov_b32_e32 v238, v2
	v_mov_b32_e32 v239, v3
	s_nop 1
	v_permlane32_swap_b32_e32 v236, v238
	v_permlane32_swap_b32_e32 v237, v239
	global_store_dwordx4 v[200:201], v[236:239], off sc1
	s_nop 1
	v_mov_b64_e32 v[2:3], v[172:173]
	v_mov_b64_e32 v[4:5], v[174:175]
	v_lshl_add_u64 v[14:15], v[20:21], 0, s[0:1]
	s_mov_b64 s[0:1], 0xf0
	v_pk_mul_f32 v[2:3], v[12:13], v[2:3]
	v_pk_mul_f32 v[4:5], v[10:11], v[4:5]
	v_cvt_pk_bf16_f32 v2, v2, v3
	v_cvt_pk_bf16_f32 v3, v4, v5
	v_mov_b32_e32 v236, v2
	v_mov_b32_e32 v237, v3
	v_mov_b64_e32 v[200:201], v[14:15]
	s_nop 1
	v_mov_b64_e32 v[2:3], v[176:177]
	v_mov_b64_e32 v[4:5], v[178:179]
	v_pk_mul_f32 v[2:3], v[6:7], v[2:3]
	v_pk_mul_f32 v[4:5], v[8:9], v[4:5]
	v_cvt_pk_bf16_f32 v2, v2, v3
	v_cvt_pk_bf16_f32 v3, v4, v5
	v_lshl_add_u64 v[4:5], v[20:21], 0, s[0:1]
	v_mov_b32_e32 v238, v2
	v_mov_b32_e32 v239, v3
	s_nop 1
	v_permlane32_swap_b32_e32 v236, v238
	v_permlane32_swap_b32_e32 v237, v239
	global_store_dwordx4 v[200:201], v[236:239], off sc1
	s_nop 1
	s_branch .LBB0_1595

.LBB0_2167:
	s_cmpk_gt_u32 s0, 0xff
	s_waitcnt lgkmcnt(0)
	s_barrier
	s_cbranch_scc1 .LBB0_2148
	s_lshl_b32 s0, s0, 8
	v_lshl_add_u32 v5, v207, 2, 0
	s_and_b32 s1, s0, 0xc000
	v_add_u32_e32 v6, s1, v5
	ds_read2st64_b32 v[10:11], v6 offset1:1
	ds_read2st64_b32 v[14:15], v6 offset0:2 offset1:3
	ds_read2st64_b32 v[86:87], v6 offset0:4 offset1:5
	ds_read2st64_b32 v[88:89], v6 offset0:6 offset1:7
	ds_read2st64_b32 v[90:91], v6 offset0:8 offset1:9
	ds_read2st64_b32 v[92:93], v6 offset0:10 offset1:11
	ds_read2st64_b32 v[94:95], v6 offset0:12 offset1:13
	ds_read2st64_b32 v[96:97], v6 offset0:14 offset1:15
	ds_read2st64_b32 v[98:99], v6 offset0:16 offset1:17
	ds_read2st64_b32 v[100:101], v6 offset0:18 offset1:19
	ds_read2st64_b32 v[102:103], v6 offset0:20 offset1:21
	ds_read2st64_b32 v[104:105], v6 offset0:22 offset1:23
	ds_read2st64_b32 v[106:107], v6 offset0:24 offset1:25
	ds_read2st64_b32 v[108:109], v6 offset0:26 offset1:27
	ds_read2st64_b32 v[110:111], v6 offset0:28 offset1:29
	ds_read2st64_b32 v[112:113], v6 offset0:30 offset1:31
	ds_read2st64_b32 v[114:115], v6 offset0:32 offset1:33
	ds_read2st64_b32 v[116:117], v6 offset0:34 offset1:35
	ds_read2st64_b32 v[118:119], v6 offset0:36 offset1:37
	ds_read2st64_b32 v[120:121], v6 offset0:38 offset1:39
	ds_read2st64_b32 v[122:123], v6 offset0:40 offset1:41
	ds_read2st64_b32 v[124:125], v6 offset0:42 offset1:43
	ds_read2st64_b32 v[126:127], v6 offset0:44 offset1:45
	ds_read2st64_b32 v[128:129], v6 offset0:46 offset1:47
	ds_read2st64_b32 v[12:13], v6 offset0:56 offset1:57
	ds_read2st64_b32 v[130:131], v6 offset0:58 offset1:59
	ds_read2st64_b32 v[2:3], v6 offset0:60 offset1:61
	ds_read_b32 v4, v6 offset:15872
	s_waitcnt lgkmcnt(14)
	v_pk_mul_f32 v[10:11], v[160:161], v[10:11]
	s_or_b32 s0, s0, 0x3f00
	v_pk_fma_f32 v[82:83], v[64:65], v[0:1], v[10:11] op_sel_hi:[1,0,1] neg_lo:[0,0,1] neg_hi:[0,0,1]
	v_pk_mul_f32 v[10:11], v[160:161], v[88:89]
	v_add_u32_e32 v5, s0, v5
	v_pk_fma_f32 v[70:71], v[70:71], v[0:1], v[10:11] op_sel_hi:[1,0,1] neg_lo:[0,0,1] neg_hi:[0,0,1]
	v_pk_mul_f32 v[10:11], v[160:161], v[86:87]
	ds_read_b32 v5, v5
	ds_read2st64_b32 v[132:133], v6 offset0:48 offset1:49
	ds_read2st64_b32 v[134:135], v6 offset0:50 offset1:51
	ds_read2st64_b32 v[136:137], v6 offset0:52 offset1:53
	ds_read2st64_b32 v[138:139], v6 offset0:54 offset1:55
	v_pk_fma_f32 v[86:87], v[68:69], v[0:1], v[10:11] op_sel_hi:[1,0,1] neg_lo:[0,0,1] neg_hi:[0,0,1]
	v_pk_mul_f32 v[10:11], v[160:161], v[92:93]
	s_waitcnt lgkmcnt(6)
	v_pk_mul_f32 v[2:3], v[160:161], v[2:3]
	v_pk_fma_f32 v[74:75], v[74:75], v[0:1], v[10:11] op_sel_hi:[1,0,1] neg_lo:[0,0,1] neg_hi:[0,0,1]
	v_pk_mul_f32 v[10:11], v[160:161], v[90:91]
	v_pk_fma_f32 v[6:7], v[28:29], v[0:1], v[2:3] op_sel_hi:[1,0,1] neg_lo:[0,0,1] neg_hi:[0,0,1]
	v_pk_fma_f32 v[90:91], v[72:73], v[0:1], v[10:11] op_sel_hi:[1,0,1] neg_lo:[0,0,1] neg_hi:[0,0,1]
	v_pk_mul_f32 v[10:11], v[160:161], v[96:97]
	s_waitcnt lgkmcnt(4)
	v_pk_mul_f32 v[2:3], v[160:161], v[4:5]
	v_pk_fma_f32 v[68:69], v[78:79], v[0:1], v[10:11] op_sel_hi:[1,0,1] neg_lo:[0,0,1] neg_hi:[0,0,1]
	v_pk_mul_f32 v[10:11], v[160:161], v[94:95]
	v_pk_fma_f32 v[8:9], v[30:31], v[0:1], v[2:3] op_sel_hi:[1,0,1] neg_lo:[0,0,1] neg_hi:[0,0,1]
	v_pk_fma_f32 v[88:89], v[76:77], v[0:1], v[10:11] op_sel_hi:[1,0,1] neg_lo:[0,0,1] neg_hi:[0,0,1]
	v_pk_mul_f32 v[10:11], v[160:161], v[100:101]
	v_pk_mul_f32 v[14:15], v[160:161], v[14:15]
	v_pk_fma_f32 v[64:65], v[50:51], v[0:1], v[10:11] op_sel_hi:[1,0,1] neg_lo:[0,0,1] neg_hi:[0,0,1]
	v_pk_mul_f32 v[10:11], v[160:161], v[98:99]
	v_pk_fma_f32 v[66:67], v[66:67], v[0:1], v[14:15] op_sel_hi:[1,0,1] neg_lo:[0,0,1] neg_hi:[0,0,1]
	v_pk_fma_f32 v[78:79], v[48:49], v[0:1], v[10:11] op_sel_hi:[1,0,1] neg_lo:[0,0,1] neg_hi:[0,0,1]
	v_pk_mul_f32 v[10:11], v[160:161], v[104:105]
	v_pk_mul_f32 v[142:143], v[82:83], v[82:83]
	v_pk_fma_f32 v[54:55], v[54:55], v[0:1], v[10:11] op_sel_hi:[1,0,1] neg_lo:[0,0,1] neg_hi:[0,0,1]
	v_pk_mul_f32 v[10:11], v[160:161], v[102:103]
	v_pk_mul_f32 v[12:13], v[160:161], v[12:13]
	v_pk_fma_f32 v[76:77], v[52:53], v[0:1], v[10:11] op_sel_hi:[1,0,1] neg_lo:[0,0,1] neg_hi:[0,0,1]
	v_pk_mul_f32 v[10:11], v[160:161], v[108:109]
	global_load_dwordx4 v[2:5], v164, s[38:39] offset:512
	global_load_dwordx4 v[152:155], v164, s[38:39] offset:544
	global_load_dwordx4 v[156:159], v164, s[38:39] offset:576
	global_load_dwordx4 v[168:171], v164, s[38:39] offset:608
	global_load_dwordx4 v[172:175], v164, s[38:39] offset:640
	global_load_dwordx4 v[176:179], v164, s[38:39] offset:672
	global_load_dwordx4 v[180:183], v164, s[38:39] offset:704
	global_load_dwordx4 v[184:187], v164, s[38:39] offset:736
	global_load_dwordx4 v[188:191], v164, s[38:39] offset:768
	global_load_dwordx4 v[192:195], v164, s[38:39] offset:800
	global_load_dwordx4 v[196:199], v164, s[38:39] offset:832
	v_pk_fma_f32 v[50:51], v[58:59], v[0:1], v[10:11] op_sel_hi:[1,0,1] neg_lo:[0,0,1] neg_hi:[0,0,1]
	v_pk_mul_f32 v[10:11], v[160:161], v[106:107]
	v_pk_mul_f32 v[140:141], v[66:67], v[66:67]
	v_pk_fma_f32 v[72:73], v[56:57], v[0:1], v[10:11] op_sel_hi:[1,0,1] neg_lo:[0,0,1] neg_hi:[0,0,1]
	v_pk_mul_f32 v[10:11], v[160:161], v[112:113]
	v_pk_fma_f32 v[12:13], v[24:25], v[0:1], v[12:13] op_sel_hi:[1,0,1] neg_lo:[0,0,1] neg_hi:[0,0,1]
	v_pk_fma_f32 v[48:49], v[62:63], v[0:1], v[10:11] op_sel_hi:[1,0,1] neg_lo:[0,0,1] neg_hi:[0,0,1]
	v_pk_mul_f32 v[10:11], v[160:161], v[110:111]
	v_pk_mul_f32 v[146:147], v[86:87], v[86:87]
	v_pk_fma_f32 v[58:59], v[60:61], v[0:1], v[10:11] op_sel_hi:[1,0,1] neg_lo:[0,0,1] neg_hi:[0,0,1]
	v_pk_mul_f32 v[10:11], v[160:161], v[116:117]
	v_pk_mul_f32 v[144:145], v[70:71], v[70:71]
	v_pk_fma_f32 v[34:35], v[34:35], v[0:1], v[10:11] op_sel_hi:[1,0,1] neg_lo:[0,0,1] neg_hi:[0,0,1]
	v_pk_mul_f32 v[10:11], v[160:161], v[114:115]
	v_pk_mul_f32 v[148:149], v[90:91], v[90:91]
	v_pk_fma_f32 v[56:57], v[32:33], v[0:1], v[10:11] op_sel_hi:[1,0,1] neg_lo:[0,0,1] neg_hi:[0,0,1]
	v_pk_mul_f32 v[10:11], v[160:161], v[120:121]
	v_pk_mul_f32 v[92:93], v[74:75], v[74:75]
	v_pk_fma_f32 v[32:33], v[38:39], v[0:1], v[10:11] op_sel_hi:[1,0,1] neg_lo:[0,0,1] neg_hi:[0,0,1]
	v_pk_mul_f32 v[10:11], v[160:161], v[118:119]
	v_pk_mul_f32 v[94:95], v[88:89], v[88:89]
	v_pk_fma_f32 v[52:53], v[36:37], v[0:1], v[10:11] op_sel_hi:[1,0,1] neg_lo:[0,0,1] neg_hi:[0,0,1]
	v_pk_mul_f32 v[10:11], v[160:161], v[124:125]
	v_pk_mul_f32 v[96:97], v[68:69], v[68:69]
	v_pk_fma_f32 v[30:31], v[42:43], v[0:1], v[10:11] op_sel_hi:[1,0,1] neg_lo:[0,0,1] neg_hi:[0,0,1]
	v_pk_mul_f32 v[10:11], v[160:161], v[122:123]
	v_pk_mul_f32 v[98:99], v[78:79], v[78:79]
	v_pk_fma_f32 v[40:41], v[40:41], v[0:1], v[10:11] op_sel_hi:[1,0,1] neg_lo:[0,0,1] neg_hi:[0,0,1]
	v_pk_mul_f32 v[10:11], v[160:161], v[128:129]
	v_pk_mul_f32 v[100:101], v[64:65], v[64:65]
	v_pk_fma_f32 v[28:29], v[46:47], v[0:1], v[10:11] op_sel_hi:[1,0,1] neg_lo:[0,0,1] neg_hi:[0,0,1]
	v_pk_mul_f32 v[10:11], v[160:161], v[126:127]
	v_pk_mul_f32 v[102:103], v[76:77], v[76:77]
	v_pk_fma_f32 v[38:39], v[44:45], v[0:1], v[10:11] op_sel_hi:[1,0,1] neg_lo:[0,0,1] neg_hi:[0,0,1]
	s_waitcnt lgkmcnt(2)
	v_pk_mul_f32 v[10:11], v[160:161], v[134:135]
	v_pk_mul_f32 v[104:105], v[54:55], v[54:55]
	v_pk_fma_f32 v[18:19], v[18:19], v[0:1], v[10:11] op_sel_hi:[1,0,1] neg_lo:[0,0,1] neg_hi:[0,0,1]
	v_pk_mul_f32 v[10:11], v[160:161], v[132:133]
	v_pk_mul_f32 v[106:107], v[72:73], v[72:73]
	v_pk_fma_f32 v[36:37], v[16:17], v[0:1], v[10:11] op_sel_hi:[1,0,1] neg_lo:[0,0,1] neg_hi:[0,0,1]
	s_waitcnt lgkmcnt(0)
	v_pk_mul_f32 v[10:11], v[160:161], v[138:139]
	v_pk_mul_f32 v[108:109], v[50:51], v[50:51]
	v_pk_fma_f32 v[14:15], v[22:23], v[0:1], v[10:11] op_sel_hi:[1,0,1] neg_lo:[0,0,1] neg_hi:[0,0,1]
	v_pk_mul_f32 v[10:11], v[160:161], v[136:137]
	v_pk_mul_f32 v[60:61], v[58:59], v[58:59]
	v_pk_fma_f32 v[16:17], v[20:21], v[0:1], v[10:11] op_sel_hi:[1,0,1] neg_lo:[0,0,1] neg_hi:[0,0,1]
	v_pk_mul_f32 v[10:11], v[160:161], v[130:131]
	v_pk_mul_f32 v[62:63], v[48:49], v[48:49]
	v_pk_fma_f32 v[10:11], v[26:27], v[0:1], v[10:11] op_sel_hi:[1,0,1] neg_lo:[0,0,1] neg_hi:[0,0,1]
	v_add_f32_e32 v0, v142, v143
	v_add_f32_e32 v0, v0, v140
	v_add_f32_e32 v0, v0, v141
	v_add_f32_e32 v0, v0, v146
	v_add_f32_e32 v0, v0, v147
	v_add_f32_e32 v0, v0, v144
	v_add_f32_e32 v0, v0, v145
	v_add_f32_e32 v0, v0, v148
	v_add_f32_e32 v0, v0, v149
	v_add_f32_e32 v0, v0, v92
	v_add_f32_e32 v0, v0, v93
	v_add_f32_e32 v0, v0, v94
	v_add_f32_e32 v0, v0, v95
	v_add_f32_e32 v0, v0, v96
	v_add_f32_e32 v0, v0, v97
	v_add_f32_e32 v0, v0, v98
	v_add_f32_e32 v0, v0, v99
	v_add_f32_e32 v0, v0, v100
	v_add_f32_e32 v0, v0, v101
	v_add_f32_e32 v0, v0, v102
	v_add_f32_e32 v0, v0, v103
	v_add_f32_e32 v0, v0, v104
	v_add_f32_e32 v0, v0, v105
	v_add_f32_e32 v0, v0, v106
	v_add_f32_e32 v0, v0, v107
	v_add_f32_e32 v0, v0, v108
	v_add_f32_e32 v0, v0, v109
	v_add_f32_e32 v0, v0, v60
	v_add_f32_e32 v0, v0, v61
	v_add_f32_e32 v0, v0, v62
	v_pk_mul_f32 v[112:113], v[56:57], v[56:57]
	v_add_f32_e32 v0, v0, v63
	v_add_f32_e32 v0, v0, v112
	v_pk_mul_f32 v[110:111], v[34:35], v[34:35]
	v_add_f32_e32 v0, v0, v113
	v_add_f32_e32 v0, v0, v110
	v_pk_mul_f32 v[116:117], v[52:53], v[52:53]
	v_add_f32_e32 v0, v0, v111
	v_add_f32_e32 v0, v0, v116
	v_pk_mul_f32 v[114:115], v[32:33], v[32:33]
	v_add_f32_e32 v0, v0, v117
	v_add_f32_e32 v0, v0, v114
	v_pk_mul_f32 v[118:119], v[40:41], v[40:41]
	v_add_f32_e32 v0, v0, v115
	v_add_f32_e32 v0, v0, v118
	v_pk_mul_f32 v[42:43], v[30:31], v[30:31]
	v_add_f32_e32 v0, v0, v119
	v_add_f32_e32 v0, v0, v42
	v_pk_mul_f32 v[44:45], v[38:39], v[38:39]
	v_add_f32_e32 v0, v0, v43
	v_add_f32_e32 v0, v0, v44
	v_pk_mul_f32 v[46:47], v[28:29], v[28:29]
	v_add_f32_e32 v0, v0, v45
	v_add_f32_e32 v0, v0, v46
	v_pk_mul_f32 v[122:123], v[36:37], v[36:37]
	v_add_f32_e32 v0, v0, v47
	v_add_f32_e32 v0, v0, v122
	v_pk_mul_f32 v[120:121], v[18:19], v[18:19]
	v_add_f32_e32 v0, v0, v123
	v_add_f32_e32 v0, v0, v120
	v_pk_mul_f32 v[20:21], v[16:17], v[16:17]
	v_add_f32_e32 v0, v0, v121
	v_add_f32_e32 v0, v0, v20
	v_pk_mul_f32 v[22:23], v[14:15], v[14:15]
	v_add_f32_e32 v0, v0, v21
	v_add_f32_e32 v0, v0, v22
	v_pk_mul_f32 v[24:25], v[12:13], v[12:13]
	v_add_f32_e32 v0, v0, v23
	v_add_f32_e32 v0, v0, v24
	v_pk_mul_f32 v[26:27], v[10:11], v[10:11]
	v_add_f32_e32 v0, v0, v25
	v_add_f32_e32 v0, v0, v26
	v_pk_mul_f32 v[80:81], v[6:7], v[6:7]
	v_add_f32_e32 v0, v0, v27
	v_add_f32_e32 v0, v0, v80
	v_pk_mul_f32 v[84:85], v[8:9], v[8:9]
	v_add_f32_e32 v0, v0, v81
	v_add_f32_e32 v0, v0, v84
	v_add_f32_e32 v22, v0, v85
	ds_bpermute_b32 v23, v165, v22
	v_lshlrev_b32_e32 v0, 1, v162
	v_lshl_add_u64 v[20:21], s[46:47], 0, v[0:1]
	v_lshl_add_u64 v[20:21], v[20:21], 0, v[166:167]
	s_waitcnt lgkmcnt(0)
	v_add_f32_e32 v0, v22, v23
	v_fmamk_f32 v0, v0, 0x3c000000, v205
	v_mul_f32_e32 v22, 0x4b800000, v0
	v_cmp_gt_f32_e32 vcc, s65, v0
	s_nop 1
	v_cndmask_b32_e32 v0, v0, v22, vcc
	v_rsq_f32_e32 v22, v0
	v_lshlrev_b32_e32 v0, 4, v163
	v_lshl_add_u64 v[20:21], v[20:21], 0, v[0:1]
	v_mul_f32_e32 v0, 0x45800000, v22
	v_cndmask_b32_e32 v0, v22, v0, vcc
	v_mul_f32_e32 v0, 0x3ee34c56, v0
	v_pk_mul_f32 v[22:23], v[82:83], v[0:1] op_sel_hi:[1,0]
	v_pk_mul_f32 v[24:25], v[86:87], v[0:1] op_sel_hi:[1,0]
	s_waitcnt vmcnt(0)
	v_pk_mul_f32 v[2:3], v[2:3], v[22:23]
	v_pk_mul_f32 v[22:23], v[66:67], v[0:1] op_sel_hi:[1,0]
	v_cvt_pk_bf16_f32 v2, v2, v3
	v_pk_mul_f32 v[4:5], v[4:5], v[22:23]
	v_lshl_add_u64 v[22:23], v[20:21], 0, 16
	v_cvt_pk_bf16_f32 v3, v4, v5
	v_mov_b32_e32 v236, v2
	v_mov_b32_e32 v237, v3
	v_mov_b64_e32 v[200:201], v[20:21]
	s_nop 1
	v_mov_b64_e32 v[2:3], v[152:153]
	v_mov_b64_e32 v[4:5], v[154:155]
	v_pk_mul_f32 v[26:27], v[74:75], v[0:1] op_sel_hi:[1,0]
	v_pk_mul_f32 v[18:19], v[18:19], v[0:1] op_sel_hi:[1,0]
	v_pk_mul_f32 v[16:17], v[16:17], v[0:1] op_sel_hi:[1,0]
	v_pk_mul_f32 v[14:15], v[14:15], v[0:1] op_sel_hi:[1,0]
	v_pk_mul_f32 v[12:13], v[12:13], v[0:1] op_sel_hi:[1,0]
	v_pk_mul_f32 v[10:11], v[10:11], v[0:1] op_sel_hi:[1,0]
	v_pk_mul_f32 v[6:7], v[6:7], v[0:1] op_sel_hi:[1,0]
	v_pk_mul_f32 v[8:9], v[8:9], v[0:1] op_sel_hi:[1,0]
	v_pk_mul_f32 v[2:3], v[2:3], v[24:25]
	v_pk_mul_f32 v[24:25], v[70:71], v[0:1] op_sel_hi:[1,0]
	v_cvt_pk_bf16_f32 v2, v2, v3
	v_pk_mul_f32 v[4:5], v[4:5], v[24:25]
	v_pk_mul_f32 v[24:25], v[90:91], v[0:1] op_sel_hi:[1,0]
	v_cvt_pk_bf16_f32 v3, v4, v5
	v_mov_b32_e32 v238, v2
	v_mov_b32_e32 v239, v3
	s_nop 1
	v_permlane32_swap_b32_e32 v236, v238
	v_permlane32_swap_b32_e32 v237, v239
	global_store_dwordx4 v[200:201], v[236:239], off sc1
	s_nop 1
	v_mov_b64_e32 v[2:3], v[156:157]
	v_mov_b64_e32 v[4:5], v[158:159]
	v_lshl_add_u64 v[22:23], v[20:21], 0, 32
	v_pk_mul_f32 v[2:3], v[2:3], v[24:25]
	v_pk_mul_f32 v[4:5], v[4:5], v[26:27]
	v_cvt_pk_bf16_f32 v2, v2, v3
	v_cvt_pk_bf16_f32 v3, v4, v5
	v_mov_b32_e32 v236, v2
	v_mov_b32_e32 v237, v3
	v_mov_b64_e32 v[200:201], v[22:23]
	s_nop 1
	v_mov_b64_e32 v[2:3], v[168:169]
	v_mov_b64_e32 v[4:5], v[170:171]
	v_pk_mul_f32 v[24:25], v[88:89], v[0:1] op_sel_hi:[1,0]
	v_pk_mul_f32 v[26:27], v[68:69], v[0:1] op_sel_hi:[1,0]
	v_lshl_add_u64 v[22:23], v[20:21], 0, 48
	v_pk_mul_f32 v[2:3], v[2:3], v[24:25]
	v_pk_mul_f32 v[4:5], v[4:5], v[26:27]
	v_cvt_pk_bf16_f32 v2, v2, v3
	v_cvt_pk_bf16_f32 v3, v4, v5
	v_mov_b32_e32 v238, v2
	v_mov_b32_e32 v239, v3
	s_nop 1
	v_permlane32_swap_b32_e32 v236, v238
	v_permlane32_swap_b32_e32 v237, v239
	global_store_dwordx4 v[200:201], v[236:239], off sc1
	s_nop 1
	v_mov_b64_e32 v[2:3], v[172:173]
	v_mov_b64_e32 v[4:5], v[174:175]
	v_pk_mul_f32 v[24:25], v[78:79], v[0:1] op_sel_hi:[1,0]
	v_pk_mul_f32 v[26:27], v[64:65], v[0:1] op_sel_hi:[1,0]
	v_lshl_add_u64 v[22:23], v[20:21], 0, 64
	v_pk_mul_f32 v[2:3], v[2:3], v[24:25]
	v_pk_mul_f32 v[4:5], v[4:5], v[26:27]
	v_cvt_pk_bf16_f32 v2, v2, v3
	v_cvt_pk_bf16_f32 v3, v4, v5
	v_mov_b32_e32 v236, v2
	v_mov_b32_e32 v237, v3
	v_mov_b64_e32 v[200:201], v[22:23]
	s_nop 1
	v_mov_b64_e32 v[2:3], v[176:177]
	v_mov_b64_e32 v[4:5], v[178:179]
	global_load_dwordx4 v[152:155], v164, s[38:39] offset:864
	global_load_dwordx4 v[156:159], v164, s[38:39] offset:896
	global_load_dwordx4 v[168:171], v164, s[38:39] offset:928
	global_load_dwordx4 v[172:175], v164, s[38:39] offset:960
	global_load_dwordx4 v[176:179], v164, s[38:39] offset:992
	v_pk_mul_f32 v[24:25], v[76:77], v[0:1] op_sel_hi:[1,0]
	v_pk_mul_f32 v[26:27], v[54:55], v[0:1] op_sel_hi:[1,0]
	v_lshl_add_u64 v[22:23], v[20:21], 0, s[28:29]
	v_pk_mul_f32 v[2:3], v[2:3], v[24:25]
	v_pk_mul_f32 v[4:5], v[4:5], v[26:27]
	v_cvt_pk_bf16_f32 v2, v2, v3
	v_cvt_pk_bf16_f32 v3, v4, v5
	v_mov_b32_e32 v238, v2
	v_mov_b32_e32 v239, v3
	s_nop 1
	v_permlane32_swap_b32_e32 v236, v238
	v_permlane32_swap_b32_e32 v237, v239
	global_store_dwordx4 v[200:201], v[236:239], off sc1
	s_nop 1
	v_mov_b64_e32 v[2:3], v[180:181]
	v_mov_b64_e32 v[4:5], v[182:183]
	v_pk_mul_f32 v[24:25], v[72:73], v[0:1] op_sel_hi:[1,0]
	v_pk_mul_f32 v[26:27], v[50:51], v[0:1] op_sel_hi:[1,0]
	v_lshl_add_u64 v[22:23], v[20:21], 0, s[36:37]
	v_pk_mul_f32 v[2:3], v[2:3], v[24:25]
	v_pk_mul_f32 v[4:5], v[4:5], v[26:27]
	v_cvt_pk_bf16_f32 v2, v2, v3
	v_cvt_pk_bf16_f32 v3, v4, v5
	v_mov_b32_e32 v236, v2
	v_mov_b32_e32 v237, v3
	v_mov_b64_e32 v[200:201], v[22:23]
	s_nop 1
	v_mov_b64_e32 v[2:3], v[184:185]
	v_mov_b64_e32 v[4:5], v[186:187]
	v_pk_mul_f32 v[24:25], v[58:59], v[0:1] op_sel_hi:[1,0]
	v_pk_mul_f32 v[26:27], v[48:49], v[0:1] op_sel_hi:[1,0]
	v_lshl_add_u64 v[22:23], v[20:21], 0, s[40:41]
	v_pk_mul_f32 v[2:3], v[24:25], v[2:3]
	v_pk_mul_f32 v[4:5], v[26:27], v[4:5]
	v_cvt_pk_bf16_f32 v2, v2, v3
	v_cvt_pk_bf16_f32 v3, v4, v5
	v_mov_b32_e32 v238, v2
	v_mov_b32_e32 v239, v3
	s_nop 1
	v_permlane32_swap_b32_e32 v236, v238
	v_permlane32_swap_b32_e32 v237, v239
	global_store_dwordx4 v[200:201], v[236:239], off sc1
	s_nop 1
	v_mov_b64_e32 v[2:3], v[188:189]
	v_mov_b64_e32 v[4:5], v[190:191]
	v_pk_mul_f32 v[24:25], v[56:57], v[0:1] op_sel_hi:[1,0]
	v_pk_mul_f32 v[26:27], v[34:35], v[0:1] op_sel_hi:[1,0]
	v_lshl_add_u64 v[22:23], v[20:21], 0, s[52:53]
	v_pk_mul_f32 v[2:3], v[24:25], v[2:3]
	v_pk_mul_f32 v[4:5], v[26:27], v[4:5]
	v_cvt_pk_bf16_f32 v2, v2, v3
	v_cvt_pk_bf16_f32 v3, v4, v5
	v_mov_b32_e32 v236, v2
	v_mov_b32_e32 v237, v3
	v_mov_b64_e32 v[200:201], v[22:23]
	s_nop 1
	v_mov_b64_e32 v[2:3], v[192:193]
	v_mov_b64_e32 v[4:5], v[194:195]
	v_pk_mul_f32 v[24:25], v[52:53], v[0:1] op_sel_hi:[1,0]
	v_pk_mul_f32 v[26:27], v[32:33], v[0:1] op_sel_hi:[1,0]
	v_lshl_add_u64 v[22:23], v[20:21], 0, s[54:55]
	v_pk_mul_f32 v[2:3], v[24:25], v[2:3]
	v_pk_mul_f32 v[4:5], v[26:27], v[4:5]
	v_cvt_pk_bf16_f32 v2, v2, v3
	v_cvt_pk_bf16_f32 v3, v4, v5
	v_mov_b32_e32 v238, v2
	v_mov_b32_e32 v239, v3
	s_nop 1
	v_permlane32_swap_b32_e32 v236, v238
	v_permlane32_swap_b32_e32 v237, v239
	global_store_dwordx4 v[200:201], v[236:239], off sc1
	s_nop 1
	v_mov_b64_e32 v[2:3], v[196:197]
	v_mov_b64_e32 v[4:5], v[198:199]
	v_pk_mul_f32 v[24:25], v[40:41], v[0:1] op_sel_hi:[1,0]
	v_pk_mul_f32 v[26:27], v[30:31], v[0:1] op_sel_hi:[1,0]
	v_lshl_add_u64 v[22:23], v[20:21], 0, s[56:57]
	v_pk_mul_f32 v[2:3], v[24:25], v[2:3]
	v_pk_mul_f32 v[4:5], v[26:27], v[4:5]
	v_cvt_pk_bf16_f32 v2, v2, v3
	v_cvt_pk_bf16_f32 v3, v4, v5
	v_mov_b32_e32 v236, v2
	v_mov_b32_e32 v237, v3
	v_mov_b64_e32 v[200:201], v[22:23]
	s_nop 1
	s_waitcnt vmcnt(6)
	v_mov_b64_e32 v[2:3], v[152:153]
	v_mov_b64_e32 v[4:5], v[154:155]
	v_pk_mul_f32 v[24:25], v[38:39], v[0:1] op_sel_hi:[1,0]
	v_pk_mul_f32 v[26:27], v[28:29], v[0:1] op_sel_hi:[1,0]
	v_lshl_add_u64 v[22:23], v[20:21], 0, s[58:59]
	v_pk_mul_f32 v[2:3], v[24:25], v[2:3]
	v_pk_mul_f32 v[4:5], v[26:27], v[4:5]
	v_cvt_pk_bf16_f32 v2, v2, v3
	v_cvt_pk_bf16_f32 v3, v4, v5
	v_mov_b32_e32 v238, v2
	v_mov_b32_e32 v239, v3
	s_nop 1
	v_permlane32_swap_b32_e32 v236, v238
	v_permlane32_swap_b32_e32 v237, v239
	global_store_dwordx4 v[200:201], v[236:239], off sc1
	s_nop 1
	v_mov_b64_e32 v[2:3], v[156:157]
	v_mov_b64_e32 v[4:5], v[158:159]
	v_pk_mul_f32 v[24:25], v[36:37], v[0:1] op_sel_hi:[1,0]
	v_lshl_add_u64 v[22:23], v[20:21], 0, s[70:71]
	v_pk_mul_f32 v[2:3], v[24:25], v[2:3]
	v_pk_mul_f32 v[4:5], v[18:19], v[4:5]
	v_cvt_pk_bf16_f32 v2, v2, v3
	v_cvt_pk_bf16_f32 v3, v4, v5
	v_mov_b32_e32 v236, v2
	v_mov_b32_e32 v237, v3
	v_mov_b64_e32 v[200:201], v[22:23]
	s_nop 1
	v_mov_b64_e32 v[2:3], v[168:169]
	v_mov_b64_e32 v[4:5], v[170:171]
	v_lshl_add_u64 v[18:19], v[20:21], 0, s[72:73]
	v_pk_mul_f32 v[2:3], v[16:17], v[2:3]
	v_pk_mul_f32 v[4:5], v[14:15], v[4:5]
	v_cvt_pk_bf16_f32 v2, v2, v3
	v_cvt_pk_bf16_f32 v3, v4, v5
	v_mov_b32_e32 v238, v2
	v_mov_b32_e32 v239, v3
	s_nop 1
	v_permlane32_swap_b32_e32 v236, v238
	v_permlane32_swap_b32_e32 v237, v239
	global_store_dwordx4 v[200:201], v[236:239], off sc1
	s_nop 1
	v_mov_b64_e32 v[2:3], v[172:173]
	v_mov_b64_e32 v[4:5], v[174:175]
	v_lshl_add_u64 v[14:15], v[20:21], 0, s[74:75]
	v_pk_mul_f32 v[2:3], v[12:13], v[2:3]
	v_pk_mul_f32 v[4:5], v[10:11], v[4:5]
	v_cvt_pk_bf16_f32 v2, v2, v3
	v_cvt_pk_bf16_f32 v3, v4, v5
	v_mov_b32_e32 v236, v2
	v_mov_b32_e32 v237, v3
	v_mov_b64_e32 v[200:201], v[14:15]
	s_nop 1
	v_mov_b64_e32 v[2:3], v[176:177]
	v_mov_b64_e32 v[4:5], v[178:179]
	v_pk_mul_f32 v[2:3], v[6:7], v[2:3]
	v_pk_mul_f32 v[4:5], v[8:9], v[4:5]
	v_cvt_pk_bf16_f32 v2, v2, v3
	v_cvt_pk_bf16_f32 v3, v4, v5
	v_lshl_add_u64 v[4:5], v[20:21], 0, s[76:77]
	v_mov_b32_e32 v238, v2
	v_mov_b32_e32 v239, v3
	s_nop 1
	v_permlane32_swap_b32_e32 v236, v238
	v_permlane32_swap_b32_e32 v237, v239
	global_store_dwordx4 v[200:201], v[236:239], off sc1
	s_nop 1
	s_branch .LBB0_2148

	.amdhsa_kernel _Z8yoco_fwd4Args
		.amdhsa_group_segment_fixed_size 0
		.amdhsa_private_segment_fixed_size 0
		.amdhsa_kernarg_size 432
		.amdhsa_user_sgpr_count 2
		.amdhsa_user_sgpr_dispatch_ptr 0
		.amdhsa_user_sgpr_queue_ptr 0
		.amdhsa_user_sgpr_kernarg_segment_ptr 1
		.amdhsa_user_sgpr_dispatch_id 0
		.amdhsa_user_sgpr_kernarg_preload_length 0
		.amdhsa_user_sgpr_kernarg_preload_offset 0
		.amdhsa_user_sgpr_private_segment_size 0
		.amdhsa_uses_dynamic_stack 0
		.amdhsa_enable_private_segment 0
		.amdhsa_system_sgpr_workgroup_id_x 1
		.amdhsa_system_sgpr_workgroup_id_y 0
		.amdhsa_system_sgpr_workgroup_id_z 0
		.amdhsa_system_sgpr_workgroup_info 0
		.amdhsa_system_vgpr_workitem_id 2
		.amdhsa_next_free_vgpr 240
		.amdhsa_next_free_sgpr 98
		.amdhsa_accum_offset 240
		.amdhsa_reserve_vcc 1
		.amdhsa_float_round_mode_32 0
		.amdhsa_float_round_mode_16_64 0
		.amdhsa_float_denorm_mode_32 3
		.amdhsa_float_denorm_mode_16_64 3
		.amdhsa_dx10_clamp 1
		.amdhsa_ieee_mode 1
		.amdhsa_fp16_overflow 0
		.amdhsa_tg_split 0
		.amdhsa_exception_fp_ieee_invalid_op 0
		.amdhsa_exception_fp_denorm_src 0
		.amdhsa_exception_fp_ieee_div_zero 0
		.amdhsa_exception_fp_ieee_overflow 0
		.amdhsa_exception_fp_ieee_underflow 0
		.amdhsa_exception_fp_ieee_inexact 0
		.amdhsa_exception_int_div_zero 0
	.end_amdhsa_kernel

amdhsa.kernels:
  - .agpr_count:     0
    .args:
      - .offset:         0
        .size:           176
        .value_kind:     by_value
      - .offset:         176
        .size:           4
        .value_kind:     hidden_block_count_x
      - .offset:         180
        .size:           4
        .value_kind:     hidden_block_count_y
      - .offset:         184
        .size:           4
        .value_kind:     hidden_block_count_z
      - .offset:         188
        .size:           2
        .value_kind:     hidden_group_size_x
      - .offset:         190
        .size:           2
        .value_kind:     hidden_group_size_y
      - .offset:         192
        .size:           2
        .value_kind:     hidden_group_size_z
      - .offset:         194
        .size:           2
        .value_kind:     hidden_remainder_x
      - .offset:         196
        .size:           2
        .value_kind:     hidden_remainder_y
      - .offset:         198
        .size:           2
        .value_kind:     hidden_remainder_z
      - .offset:         216
        .size:           8
        .value_kind:     hidden_global_offset_x
      - .offset:         224
        .size:           8
        .value_kind:     hidden_global_offset_y
      - .offset:         232
        .size:           8
        .value_kind:     hidden_global_offset_z
      - .offset:         240
        .size:           2
        .value_kind:     hidden_grid_dims
      - .offset:         264
        .size:           8
        .value_kind:     hidden_multigrid_sync_arg
      - .offset:         296
        .size:           4
        .value_kind:     hidden_dynamic_lds_size
    .group_segment_fixed_size: 0
    .kernarg_segment_align: 8
    .kernarg_segment_size: 432
    .language:       OpenCL C
    .language_version:
      - 2
      - 0
    .max_flat_workgroup_size: 512
    .name:           _Z8yoco_fwd4Args
    .private_segment_fixed_size: 0
    .sgpr_count:     104
    .sgpr_spill_count: 38
    .symbol:         _Z8yoco_fwd4Args.kd
    .uniform_work_group_size: 1
    .uses_dynamic_stack: false
    .vgpr_count:     240
    .vgpr_spill_count: 0
    .wavefront_size: 64
